# logits_job: xor-1/2/4/8 butterfly steps of the wave reductions as DPP moves instead of ds_bpermute (bit-identical sums)
# baseline (speedup 1.0000x reference)
; __device__ __forceinline__ float bflo(unsigned w) { return __uint_as_float(w << 16); }
; __device__ __forceinline__ float bfhi(unsigned w) { return __uint_as_float(w & 0xffff0000u); }
; __device__ __forceinline__ float wave_sum(float v) {
; #pragma unroll
;     for (int o = 1; o < 64; o <<= 1) v += __shfl_xor(v, o);
;     return v;
; __device__ __forceinline__ void logits_job(const Args& a, const bf16* Z, int lane, int wave) {
;     ...
;         const v2u* xr = (const v2u*)(Z + (size_t)m * D) + lane;
;         f32x4 v[4]; float s = 0.f;
; #pragma unroll
;         for (int j = 0; j < 4; ++j) { const v2u w = xr[64 * j]; v[j] = (f32x4){bflo(w.x), bfhi(w.x), bflo(w.y), bfhi(w.y)}; s += (v[j][0] + v[j][1]) + (v[j][2] + v[j][3]); }
;         const float mean = wave_sum(s) * (1.f / D); float s2 = 0.f;
; #pragma unroll
;         for (int j = 0; j < 4; ++j) { v[j] = v[j] - mean; s2 += (v[j][0] * v[j][0] + v[j][1] * v[j][1]) + (v[j][2] * v[j][2] + v[j][3] * v[j][3]); }
;         const float rstd = 1.f / sqrtf(wave_sum(s2) * (1.f / D) + LN_EPS);
;         float mine = 0.f;
; #pragma unroll
;         for (int h = 0; h < 8; ++h) { float d = 0.f;
; #pragma unroll
;             for (int j = 0; j < 4; ++j) { const f32x4 w = ((const f32x4*)(WF + h * 1024))[64 * j + lane]; d += (v[j][0] * w[0] + v[j][1] * w[1]) + (v[j][2] * w[2] + v[j][3] * w[3]); }
.LBB0_417:
	s_ashr_i32 s7, s6, 31
	s_lshl_b64 s[12:13], s[6:7], 11
	v_lshl_add_u64 v[70:71], v[0:1], 0, s[12:13]
	s_waitcnt lgkmcnt(0)
	global_load_dwordx2 v[72:73], v[70:71], off
	global_load_dwordx2 v[74:75], v[70:71], off offset:512
	global_load_dwordx2 v[96:97], v[70:71], off offset:1024
	global_load_dwordx2 v[132:133], v[70:71], off offset:1536
	global_load_dwordx4 v[100:103], v[6:7], off
	global_load_dwordx4 v[104:107], v[8:9], off
	global_load_dwordx4 v[108:111], v[10:11], off
	global_load_dwordx4 v[112:115], v[12:13], off
	global_load_dwordx4 v[116:119], v[14:15], off
	global_load_dwordx4 v[120:123], v[16:17], off
	global_load_dwordx4 v[124:127], v[18:19], off
	global_load_dwordx4 v[128:131], v[20:21], off
	s_waitcnt vmcnt(0)
	v_lshlrev_b32_e32 v79, 16, v73
	v_lshlrev_b32_e32 v78, 16, v72
	v_and_b32_e32 v83, 0xffff0000, v73
	v_and_b32_e32 v82, 0xffff0000, v72
	v_lshlrev_b32_e32 v77, 16, v75
	v_lshlrev_b32_e32 v76, 16, v74
	v_and_b32_e32 v81, 0xffff0000, v75
	v_and_b32_e32 v80, 0xffff0000, v74
	v_lshlrev_b32_e32 v95, 16, v96
	v_and_b32_e32 v98, 0xffff0000, v96
	v_lshlrev_b32_e32 v73, 16, v132
	v_and_b32_e32 v96, 0xffff0000, v132
	v_lshlrev_b32_e32 v71, 16, v133
	v_and_b32_e32 v75, 0xffff0000, v133
	v_pk_add_f32 v[132:133], v[78:79], v[82:83]
	v_pk_add_f32 v[134:135], v[76:77], v[80:81]
	v_lshlrev_b32_e32 v94, 16, v97
	v_and_b32_e32 v97, 0xffff0000, v97
	v_add_f32_e32 v72, v132, v133
	v_pk_add_f32 v[132:133], v[134:135], v[134:135] op_sel:[0,1] op_sel_hi:[1,0]
	v_add_f32_e32 v70, v95, v98
	v_add_f32_e32 v74, v94, v97
	v_add_f32_e32 v72, 0, v72
	v_mov_b32_e32 v133, v96
	v_pk_add_f32 v[134:135], v[70:71], v[74:75]
	v_pk_add_f32 v[132:133], v[72:73], v[132:133]
	s_nop 0
	v_pk_add_f32 v[132:133], v[132:133], v[134:135]
	s_nop 0
	v_add_f32_e32 v70, v132, v133
	global_load_dwordx4 v[132:135], v[22:23], off
	global_load_dwordx4 v[136:139], v[24:25], off
	s_nop 1
	v_mov_b32_dpp v72, v70 quad_perm:[1,0,3,2] row_mask:0xf bank_mask:0xf
	global_load_dwordx4 v[140:143], v[26:27], off
	global_load_dwordx4 v[144:147], v[28:29], off
	global_load_dwordx4 v[148:151], v[30:31], off
	global_load_dwordx4 v[152:155], v[32:33], off
	global_load_dwordx4 v[156:159], v[34:35], off
	s_waitcnt lgkmcnt(0)
	v_add_f32_e32 v70, v70, v72
	s_nop 1
	v_mov_b32_dpp v72, v70 quad_perm:[2,3,0,1] row_mask:0xf bank_mask:0xf
	s_waitcnt lgkmcnt(0)
	v_add_f32_e32 v70, v70, v72
	s_nop 1
	v_mov_b32_dpp v72, v70 row_shl:4 row_mask:0xf bank_mask:0x5
	v_mov_b32_dpp v72, v70 row_shr:4 row_mask:0xf bank_mask:0xa
	s_waitcnt lgkmcnt(0)
	v_add_f32_e32 v70, v70, v72
	s_nop 1
	v_mov_b32_dpp v72, v70 row_shl:8 row_mask:0xf bank_mask:0x3
	v_mov_b32_dpp v72, v70 row_shr:8 row_mask:0xf bank_mask:0xc
	s_waitcnt lgkmcnt(0)
	v_add_f32_e32 v70, v70, v72
	ds_bpermute_b32 v72, v89, v70
	s_waitcnt lgkmcnt(0)
	v_add_f32_e32 v70, v70, v72
	ds_bpermute_b32 v72, v90, v70
	s_waitcnt lgkmcnt(0)
	v_add_f32_e32 v70, v70, v72
	v_fmac_f32_e32 v83, 0xba800000, v70
	v_fmac_f32_e32 v82, 0xba800000, v70
	v_fmac_f32_e32 v81, 0xba800000, v70
	v_fmac_f32_e32 v80, 0xba800000, v70
	v_fmac_f32_e32 v79, 0xba800000, v70
	v_fmac_f32_e32 v78, 0xba800000, v70
	v_fmac_f32_e32 v77, 0xba800000, v70
	v_fmac_f32_e32 v76, 0xba800000, v70
	v_fmac_f32_e32 v94, 0xba800000, v70
	v_fmac_f32_e32 v97, 0xba800000, v70
	v_fmac_f32_e32 v95, 0xba800000, v70
	v_fmac_f32_e32 v98, 0xba800000, v70
	v_fmac_f32_e32 v71, 0xba800000, v70
	v_fmac_f32_e32 v75, 0xba800000, v70
	v_fmac_f32_e32 v73, 0xba800000, v70
	v_fmac_f32_e32 v96, 0xba800000, v70
	v_mul_f32_e32 v70, v82, v82
	v_mul_f32_e32 v72, v83, v83
	v_mul_f32_e32 v74, v80, v80
	v_mul_f32_e32 v99, v81, v81
	v_mul_f32_e32 v160, v98, v98
	v_mul_f32_e32 v161, v97, v97
	v_fmac_f32_e32 v70, v78, v78
	v_fmac_f32_e32 v72, v79, v79
	v_fmac_f32_e32 v74, v76, v76
	v_fmac_f32_e32 v99, v77, v77
	v_mul_f32_e32 v162, v96, v96
	v_mul_f32_e32 v163, v75, v75
	v_fmac_f32_e32 v160, v95, v95
	v_fmac_f32_e32 v161, v94, v94
	v_add_f32_e32 v70, v70, v72
	v_add_f32_e32 v72, v74, v99
	v_mul_f32_e32 v101, v101, v82
	v_mul_f32_e32 v103, v103, v83
	v_mul_f32_e32 v117, v82, v117
	v_mul_f32_e32 v119, v83, v119
	v_fmac_f32_e32 v162, v73, v73
	v_fmac_f32_e32 v163, v71, v71
	v_add_f32_e32 v74, v160, v161
	v_add_f32_e32 v70, v70, v72
	v_mul_f32_e32 v105, v105, v80
	v_mul_f32_e32 v107, v107, v81
	v_mul_f32_e32 v121, v80, v121
	v_mul_f32_e32 v123, v81, v123
	v_fmac_f32_e32 v101, v100, v78
	v_fmac_f32_e32 v103, v102, v79
	v_fmac_f32_e32 v117, v78, v116
	v_fmac_f32_e32 v119, v79, v118
	v_add_f32_e32 v99, v162, v163
	v_add_f32_e32 v70, v74, v70
	v_mul_f32_e32 v109, v109, v98
	v_mul_f32_e32 v111, v111, v97
	v_mul_f32_e32 v125, v98, v125
	v_mul_f32_e32 v127, v97, v127
	v_fmac_f32_e32 v105, v104, v76
	v_fmac_f32_e32 v107, v106, v77
	v_fmac_f32_e32 v121, v76, v120
	v_fmac_f32_e32 v123, v77, v122
	v_add_f32_e32 v100, v101, v103
	v_add_f32_e32 v70, v99, v70
	v_add_f32_e32 v99, v117, v119
	v_fmac_f32_e32 v109, v108, v95
	v_fmac_f32_e32 v111, v110, v94
	v_fmac_f32_e32 v125, v95, v124
	v_fmac_f32_e32 v127, v94, v126
	v_add_f32_e32 v101, v105, v107
	v_add_f32_e32 v103, v121, v123
	v_add_f32_e32 v100, 0, v100
	v_add_f32_e32 v99, 0, v99
	v_add_f32_e32 v102, v109, v111
	v_add_f32_e32 v104, v125, v127
	v_add_f32_e32 v100, v101, v100
	v_add_f32_e32 v99, v99, v103
	v_add_f32_e32 v100, v102, v100
	v_add_f32_e32 v99, v99, v104
	global_load_dwordx4 v[102:105], v[36:37], off
	global_load_dwordx4 v[106:109], v[38:39], off
	v_mul_f32_e32 v113, v96, v113
	v_mul_f32_e32 v115, v75, v115
	v_fmac_f32_e32 v113, v73, v112
	v_fmac_f32_e32 v115, v71, v114
	v_add_f32_e32 v74, v113, v115
	global_load_dwordx4 v[110:113], v[40:41], off
	global_load_dwordx4 v[114:117], v[42:43], off
	s_waitcnt vmcnt(10)
; __device__ __forceinline__ float wave_sum(float v) {
; #pragma unroll
;     for (int o = 1; o < 64; o <<= 1) v += __shfl_xor(v, o);
;     return v;
; __device__ __forceinline__ void logits_job(const Args& a, const bf16* Z, int lane, int wave) {
;     ...
;         const float mean = wave_sum(s) * (1.f / D); float s2 = 0.f;
; #pragma unroll
;         for (int j = 0; j < 4; ++j) { v[j] = v[j] - mean; s2 += (v[j][0] * v[j][0] + v[j][1] * v[j][1]) + (v[j][2] * v[j][2] + v[j][3] * v[j][3]); }
;         const float rstd = 1.f / sqrtf(wave_sum(s2) * (1.f / D) + LN_EPS);
;     ...
;         for (int h = 0; h < 8; ++h) { float d = 0.f;
; #pragma unroll
;             for (int j = 0; j < 4; ++j) { const f32x4 w = ((const f32x4*)(WF + h * 1024))[64 * j + lane]; d += (v[j][0] * w[0] + v[j][1] * w[1]) + (v[j][2] * w[2] + v[j][3] * w[3]); }
;             d = wave_sum(d); if (lane == h) mine = d; }
	v_mul_f32_e32 v118, v82, v133
	v_mul_f32_e32 v119, v83, v135
	v_fmac_f32_e32 v118, v78, v132
	v_fmac_f32_e32 v119, v79, v134
	v_add_f32_e32 v118, v118, v119
	v_add_f32_e32 v122, 0, v118
	global_load_dwordx4 v[118:121], v[44:45], off
	v_mul_f32_e32 v129, v96, v129
	v_mul_f32_e32 v101, v75, v131
	v_fmac_f32_e32 v129, v73, v128
	v_fmac_f32_e32 v101, v71, v130
	v_add_f32_e32 v101, v129, v101
	v_add_f32_e32 v74, v74, v100
	v_add_f32_e32 v99, v99, v101
	s_nop 1
	v_mov_b32_dpp v100, v74 quad_perm:[1,0,3,2] row_mask:0xf bank_mask:0xf
	s_nop 1
	v_mov_b32_dpp v101, v99 quad_perm:[1,0,3,2] row_mask:0xf bank_mask:0xf
	s_waitcnt vmcnt(10)
	v_mul_f32_e32 v123, v80, v137
	v_mul_f32_e32 v124, v81, v139
	v_fmac_f32_e32 v123, v76, v136
	s_waitcnt lgkmcnt(0)
	v_add_f32_e32 v74, v74, v100
	s_waitcnt lgkmcnt(0)
	v_add_f32_e32 v99, v99, v101
	s_nop 1
	v_mov_b32_dpp v100, v74 quad_perm:[2,3,0,1] row_mask:0xf bank_mask:0xf
	s_nop 1
	v_mov_b32_dpp v101, v99 quad_perm:[2,3,0,1] row_mask:0xf bank_mask:0xf
	v_fmac_f32_e32 v124, v77, v138
	v_add_f32_e32 v123, v123, v124
	v_add_f32_e32 v122, v122, v123
	s_waitcnt vmcnt(9)
	v_mul_f32_e32 v123, v98, v141
	v_mul_f32_e32 v124, v97, v143
	v_fmac_f32_e32 v123, v95, v140
	v_fmac_f32_e32 v124, v94, v142
	v_add_f32_e32 v123, v123, v124
	s_waitcnt lgkmcnt(0)
	v_add_f32_e32 v74, v74, v100
	s_waitcnt lgkmcnt(0)
	v_add_f32_e32 v99, v99, v101
	v_add_f32_e32 v122, v122, v123
	s_waitcnt vmcnt(8)
	v_mul_f32_e32 v123, v96, v145
	v_mul_f32_e32 v124, v75, v147
	s_nop 1
	v_mov_b32_dpp v100, v74 row_shl:4 row_mask:0xf bank_mask:0x5
	v_mov_b32_dpp v100, v74 row_shr:4 row_mask:0xf bank_mask:0xa
	s_nop 1
	v_mov_b32_dpp v101, v99 row_shl:4 row_mask:0xf bank_mask:0x5
	v_mov_b32_dpp v101, v99 row_shr:4 row_mask:0xf bank_mask:0xa
	v_fmac_f32_e32 v123, v73, v144
	v_fmac_f32_e32 v124, v71, v146
	v_add_f32_e32 v123, v123, v124
	v_add_f32_e32 v122, v122, v123
	s_nop 1
	v_mov_b32_dpp v123, v122 quad_perm:[1,0,3,2] row_mask:0xf bank_mask:0xf
	s_waitcnt lgkmcnt(0)
	v_add_f32_e32 v74, v74, v100
	s_waitcnt lgkmcnt(0)
	v_add_f32_e32 v99, v99, v101
	s_nop 1
	v_mov_b32_dpp v100, v74 row_shl:8 row_mask:0xf bank_mask:0x3
	v_mov_b32_dpp v100, v74 row_shr:8 row_mask:0xf bank_mask:0xc
	s_nop 1
	v_mov_b32_dpp v101, v99 row_shl:8 row_mask:0xf bank_mask:0x3
	v_mov_b32_dpp v101, v99 row_shr:8 row_mask:0xf bank_mask:0xc
	s_waitcnt lgkmcnt(0)
	v_add_f32_e32 v122, v122, v123
	s_nop 1
	v_mov_b32_dpp v123, v122 quad_perm:[2,3,0,1] row_mask:0xf bank_mask:0xf
	s_waitcnt vmcnt(6)
	v_mul_f32_e32 v127, v80, v153
	s_waitcnt lgkmcnt(0)
	v_add_f32_e32 v74, v74, v100
	s_waitcnt lgkmcnt(0)
	v_add_f32_e32 v101, v99, v101
	ds_bpermute_b32 v100, v89, v74
	ds_bpermute_b32 v124, v89, v101
	s_waitcnt lgkmcnt(0)
	v_add_f32_e32 v146, v122, v123
	v_mul_f32_e32 v122, v82, v149
	v_mul_f32_e32 v123, v83, v151
	v_fmac_f32_e32 v122, v78, v148
	v_fmac_f32_e32 v123, v79, v150
	v_add_f32_e32 v122, v122, v123
	v_mul_f32_e32 v128, v81, v155
	s_waitcnt lgkmcnt(0)
	v_add_f32_e32 v74, v74, v100
	s_waitcnt lgkmcnt(0)
	v_add_f32_e32 v100, v101, v124
	v_add_f32_e32 v126, 0, v122
	v_fmac_f32_e32 v127, v76, v152
	global_load_dwordx4 v[122:125], v[46:47], off
	v_fmac_f32_e32 v128, v77, v154
	v_add_f32_e32 v127, v127, v128
	v_add_f32_e32 v130, v126, v127
	s_waitcnt vmcnt(6)
	v_mul_f32_e32 v131, v98, v157
	global_load_dwordx4 v[126:129], v[48:49], off
	s_waitcnt vmcnt(6)
	v_mul_f32_e32 v103, v96, v103
	v_fmac_f32_e32 v103, v73, v102
	v_mul_f32_e32 v102, v75, v105
	v_fmac_f32_e32 v102, v71, v104
	s_waitcnt vmcnt(5)
	v_mul_f32_e32 v104, v82, v107
	v_mul_f32_e32 v105, v83, v109
	v_mul_f32_e32 v132, v97, v159
	v_fmac_f32_e32 v104, v78, v106
	v_fmac_f32_e32 v105, v79, v108
	v_fmac_f32_e32 v131, v95, v156
	v_fmac_f32_e32 v132, v94, v158
	v_add_f32_e32 v104, v104, v105
	s_waitcnt vmcnt(4)
	v_mul_f32_e32 v105, v80, v111
	v_mul_f32_e32 v106, v81, v113
	v_add_f32_e32 v131, v131, v132
	v_fmac_f32_e32 v105, v76, v110
	v_fmac_f32_e32 v106, v77, v112
	v_add_f32_e32 v138, v130, v131
	global_load_dwordx4 v[130:133], v[50:51], off
	v_add_f32_e32 v104, 0, v104
	v_add_f32_e32 v105, v105, v106
	v_add_f32_e32 v104, v104, v105
	s_waitcnt vmcnt(4)
	v_mul_f32_e32 v105, v98, v115
	v_mul_f32_e32 v106, v97, v117
	s_nop 1
	v_mov_b32_dpp v147, v146 row_shl:4 row_mask:0xf bank_mask:0x5
	v_mov_b32_dpp v147, v146 row_shr:4 row_mask:0xf bank_mask:0xa
	v_fmac_f32_e32 v105, v95, v114
	v_fmac_f32_e32 v106, v94, v116
	global_load_dwordx4 v[134:137], v[52:53], off
	v_add_f32_e32 v105, v105, v106
	v_add_f32_e32 v102, v103, v102
	v_add_f32_e32 v104, v104, v105
	s_waitcnt vmcnt(4)
	v_mul_f32_e32 v105, v96, v119
	v_add_f32_e32 v102, v138, v102
	global_load_dwordx4 v[138:141], v[54:55], off
	global_load_dwordx4 v[142:145], v[60:61], off
	v_fmac_f32_e32 v105, v73, v118
	v_mul_f32_e32 v106, v75, v121
	global_load_dwordx4 v[116:119], v[62:63], off
	v_fmac_f32_e32 v106, v71, v120
	global_load_dwordx4 v[108:111], v[56:57], off
	global_load_dwordx4 v[112:115], v[58:59], off
	v_add_f32_e32 v105, v105, v106
	s_waitcnt lgkmcnt(0)
	v_add_f32_e32 v106, v146, v147
	global_load_dwordx4 v[146:149], v[64:65], off
	global_load_dwordx4 v[150:153], v[66:67], off
	global_load_dwordx4 v[154:157], v[68:69], off
	s_nop 1
	v_mov_b32_dpp v103, v102 quad_perm:[1,0,3,2] row_mask:0xf bank_mask:0xf
	v_add_f32_e32 v104, v104, v105
	s_nop 1
	v_mov_b32_dpp v105, v104 quad_perm:[1,0,3,2] row_mask:0xf bank_mask:0xf
	s_nop 1
	v_mov_b32_dpp v72, v70 quad_perm:[1,0,3,2] row_mask:0xf bank_mask:0xf
	s_nop 1
	v_mov_b32_dpp v107, v106 row_shl:8 row_mask:0xf bank_mask:0x3
	v_mov_b32_dpp v107, v106 row_shr:8 row_mask:0xf bank_mask:0xc
	s_waitcnt lgkmcnt(0)
; __device__ __forceinline__ float wave_sum(float v) {
; #pragma unroll
;     for (int o = 1; o < 64; o <<= 1) v += __shfl_xor(v, o);
;     return v;
; __device__ __forceinline__ void logits_job(const Args& a, const bf16* Z, int lane, int wave) {
;     ...
;         for (int h = 0; h < 8; ++h) { float d = 0.f;
; #pragma unroll
;             for (int j = 0; j < 4; ++j) { const f32x4 w = ((const f32x4*)(WF + h * 1024))[64 * j + lane]; d += (v[j][0] * w[0] + v[j][1] * w[1]) + (v[j][2] * w[2] + v[j][3] * w[3]); }
;             d = wave_sum(d); if (lane == h) mine = d; }
	v_add_f32_e32 v102, v102, v103
	s_nop 1
	v_mov_b32_dpp v103, v102 quad_perm:[2,3,0,1] row_mask:0xf bank_mask:0xf
	s_waitcnt lgkmcnt(0)
	v_add_f32_e32 v104, v104, v105
	s_nop 1
	v_mov_b32_dpp v105, v104 quad_perm:[2,3,0,1] row_mask:0xf bank_mask:0xf
	s_waitcnt lgkmcnt(0)
	v_add_f32_e32 v70, v70, v72
	s_nop 1
	v_mov_b32_dpp v72, v70 quad_perm:[2,3,0,1] row_mask:0xf bank_mask:0xf
	s_waitcnt lgkmcnt(0)
	v_add_f32_e32 v102, v102, v103
	s_nop 1
	v_mov_b32_dpp v103, v102 row_shl:4 row_mask:0xf bank_mask:0x5
	v_mov_b32_dpp v103, v102 row_shr:4 row_mask:0xf bank_mask:0xa
	s_waitcnt lgkmcnt(0)
	v_add_f32_e32 v104, v104, v105
	s_nop 1
	v_mov_b32_dpp v105, v104 row_shl:4 row_mask:0xf bank_mask:0x5
	v_mov_b32_dpp v105, v104 row_shr:4 row_mask:0xf bank_mask:0xa
	s_waitcnt lgkmcnt(0)
	v_add_f32_e32 v70, v70, v72
	s_nop 1
	v_mov_b32_dpp v72, v70 row_shl:4 row_mask:0xf bank_mask:0x5
	v_mov_b32_dpp v72, v70 row_shr:4 row_mask:0xf bank_mask:0xa
	s_waitcnt lgkmcnt(0)
	v_add_f32_e32 v102, v102, v103
	s_nop 1
	v_mov_b32_dpp v103, v102 row_shl:8 row_mask:0xf bank_mask:0x3
	v_mov_b32_dpp v103, v102 row_shr:8 row_mask:0xf bank_mask:0xc
	s_waitcnt lgkmcnt(0)
	v_add_f32_e32 v104, v104, v105
	s_nop 1
	v_mov_b32_dpp v105, v104 row_shl:8 row_mask:0xf bank_mask:0x3
	v_mov_b32_dpp v105, v104 row_shr:8 row_mask:0xf bank_mask:0xc
	s_waitcnt lgkmcnt(0)
	v_add_f32_e32 v70, v70, v72
	s_nop 1
	v_mov_b32_dpp v72, v70 row_shl:8 row_mask:0xf bank_mask:0x3
	v_mov_b32_dpp v72, v70 row_shr:8 row_mask:0xf bank_mask:0xc
	s_waitcnt lgkmcnt(0)
	v_add_f32_e32 v120, v102, v103
	ds_bpermute_b32 v121, v89, v120
	s_waitcnt lgkmcnt(0)
	v_add_f32_e32 v158, v104, v105
	v_add_f32_e32 v106, v106, v107
	s_waitcnt lgkmcnt(0)
	v_add_f32_e32 v70, v70, v72
	ds_bpermute_b32 v72, v89, v70
	s_waitcnt lgkmcnt(0)
	v_add_f32_e32 v104, v120, v121
	s_waitcnt vmcnt(11)
	v_mul_f32_e32 v120, v82, v123
	v_mul_f32_e32 v121, v83, v125
	v_fmac_f32_e32 v120, v78, v122
	v_fmac_f32_e32 v121, v79, v124
	v_add_f32_e32 v120, v120, v121
	s_waitcnt vmcnt(10)
	v_mul_f32_e32 v121, v80, v127
	v_mul_f32_e32 v122, v81, v129
	v_fmac_f32_e32 v121, v76, v126
	v_fmac_f32_e32 v122, v77, v128
	v_add_f32_e32 v120, 0, v120
	v_add_f32_e32 v121, v121, v122
	v_add_f32_e32 v120, v120, v121
	ds_bpermute_b32 v107, v89, v106
	ds_bpermute_b32 v159, v89, v158
	s_waitcnt lgkmcnt(0)
	v_add_f32_e32 v70, v70, v72
	ds_bpermute_b32 v72, v90, v70
	ds_bpermute_b32 v99, v90, v74
	s_waitcnt lgkmcnt(0)
	v_add_f32_e32 v102, v106, v107
	s_waitcnt lgkmcnt(0)
	v_add_f32_e32 v106, v158, v159
	ds_bpermute_b32 v101, v90, v100
	ds_bpermute_b32 v103, v90, v102
	ds_bpermute_b32 v105, v90, v104
	s_waitcnt vmcnt(9)
	v_mul_f32_e32 v121, v98, v131
	v_mul_f32_e32 v122, v97, v133
	v_fmac_f32_e32 v121, v95, v130
	v_fmac_f32_e32 v122, v94, v132
	v_add_f32_e32 v121, v121, v122
	v_add_f32_e32 v120, v120, v121
	ds_bpermute_b32 v107, v90, v106
	s_waitcnt vmcnt(8)
	v_mul_f32_e32 v121, v96, v135
	v_mul_f32_e32 v122, v75, v137
	v_fmac_f32_e32 v121, v73, v134
	v_fmac_f32_e32 v122, v71, v136
	v_add_f32_e32 v121, v121, v122
	v_add_f32_e32 v120, v120, v121
	s_waitcnt vmcnt(7)
	v_mul_f32_e32 v122, v82, v139
	v_fmac_f32_e32 v122, v78, v138
	v_mul_f32_e32 v123, v83, v141
	v_fmac_f32_e32 v123, v79, v140
	s_waitcnt vmcnt(5)
	v_mul_f32_e32 v82, v82, v117
	v_fmac_f32_e32 v82, v78, v116
	v_mul_f32_e32 v78, v83, v119
	s_waitcnt vmcnt(4)
	v_mul_f32_e32 v109, v80, v109
	v_fmac_f32_e32 v78, v79, v118
	v_fmac_f32_e32 v109, v76, v108
	s_waitcnt vmcnt(2)
	v_mul_f32_e32 v79, v80, v147
	v_fmac_f32_e32 v79, v76, v146
	v_mul_f32_e32 v76, v81, v149
	v_mul_f32_e32 v108, v81, v111
	v_add_f32_e32 v78, v82, v78
	v_fmac_f32_e32 v76, v77, v148
	v_fmac_f32_e32 v108, v77, v110
	v_add_f32_e32 v78, 0, v78
	v_add_f32_e32 v76, v79, v76
	v_add_f32_e32 v122, v122, v123
	v_add_f32_e32 v108, v109, v108
	v_mul_f32_e32 v109, v98, v113
	v_mul_f32_e32 v110, v97, v115
	v_add_f32_e32 v76, v78, v76
	s_waitcnt vmcnt(1)
	v_mul_f32_e32 v77, v98, v151
	v_mul_f32_e32 v78, v97, v153
	v_add_f32_e32 v122, 0, v122
	v_fmac_f32_e32 v109, v95, v112
	v_fmac_f32_e32 v110, v94, v114
	v_fmac_f32_e32 v77, v95, v150
	v_fmac_f32_e32 v78, v94, v152
	v_add_f32_e32 v108, v122, v108
	v_add_f32_e32 v109, v109, v110
	v_add_f32_e32 v77, v77, v78
	v_add_f32_e32 v108, v108, v109
	v_mul_f32_e32 v109, v96, v143
	v_add_f32_e32 v76, v76, v77
	s_waitcnt vmcnt(0)
	v_mul_f32_e32 v77, v96, v155
	v_fmac_f32_e32 v109, v73, v142
	v_mul_f32_e32 v110, v75, v145
	v_fmac_f32_e32 v77, v73, v154
	v_mul_f32_e32 v73, v75, v157
	v_fmac_f32_e32 v110, v71, v144
	v_fmac_f32_e32 v73, v71, v156
	v_add_f32_e32 v109, v109, v110
	v_add_f32_e32 v71, v77, v73
	v_add_f32_e32 v108, v108, v109
	v_add_f32_e32 v71, v76, v71
	s_nop 1
	v_mov_b32_dpp v121, v120 quad_perm:[1,0,3,2] row_mask:0xf bank_mask:0xf
	s_nop 1
	v_mov_b32_dpp v109, v108 quad_perm:[1,0,3,2] row_mask:0xf bank_mask:0xf
	s_nop 1
	v_mov_b32_dpp v73, v71 quad_perm:[1,0,3,2] row_mask:0xf bank_mask:0xf
	s_waitcnt lgkmcnt(0)
	v_add_f32_e32 v75, v120, v121
	s_waitcnt lgkmcnt(0)
	v_add_f32_e32 v77, v108, v109
	s_waitcnt lgkmcnt(0)
	v_add_f32_e32 v71, v71, v73
	s_nop 1
	v_mov_b32_dpp v76, v75 quad_perm:[2,3,0,1] row_mask:0xf bank_mask:0xf
	s_nop 1
	v_mov_b32_dpp v78, v77 quad_perm:[2,3,0,1] row_mask:0xf bank_mask:0xf
	s_nop 1
	v_mov_b32_dpp v73, v71 quad_perm:[2,3,0,1] row_mask:0xf bank_mask:0xf
	s_waitcnt lgkmcnt(0)
	v_add_f32_e32 v75, v75, v76
	s_waitcnt lgkmcnt(0)
	v_add_f32_e32 v77, v77, v78
	s_waitcnt lgkmcnt(0)
	v_add_f32_e32 v71, v71, v73
	s_nop 1
	v_mov_b32_dpp v76, v75 row_shl:4 row_mask:0xf bank_mask:0x5
	v_mov_b32_dpp v76, v75 row_shr:4 row_mask:0xf bank_mask:0xa
	s_nop 1
	v_mov_b32_dpp v78, v77 row_shl:4 row_mask:0xf bank_mask:0x5
	v_mov_b32_dpp v78, v77 row_shr:4 row_mask:0xf bank_mask:0xa
	s_nop 1
	v_mov_b32_dpp v73, v71 row_shl:4 row_mask:0xf bank_mask:0x5
	v_mov_b32_dpp v73, v71 row_shr:4 row_mask:0xf bank_mask:0xa
	s_waitcnt lgkmcnt(0)
	v_add_f32_e32 v75, v75, v76
	s_waitcnt lgkmcnt(0)
	v_add_f32_e32 v77, v77, v78
	s_waitcnt lgkmcnt(0)
	v_add_f32_e32 v71, v71, v73
	s_nop 1
	v_mov_b32_dpp v76, v75 row_shl:8 row_mask:0xf bank_mask:0x3
	v_mov_b32_dpp v76, v75 row_shr:8 row_mask:0xf bank_mask:0xc
	s_nop 1
	v_mov_b32_dpp v78, v77 row_shl:8 row_mask:0xf bank_mask:0x3
	v_mov_b32_dpp v78, v77 row_shr:8 row_mask:0xf bank_mask:0xc
	s_nop 1
	v_mov_b32_dpp v73, v71 row_shl:8 row_mask:0xf bank_mask:0x3
	v_mov_b32_dpp v73, v71 row_shr:8 row_mask:0xf bank_mask:0xc
	s_waitcnt lgkmcnt(0)
	v_add_f32_e32 v75, v75, v76
	s_waitcnt lgkmcnt(0)
	v_add_f32_e32 v77, v77, v78
	s_waitcnt lgkmcnt(0)
	v_add_f32_e32 v79, v71, v73
	ds_bpermute_b32 v76, v89, v75
	ds_bpermute_b32 v78, v89, v77
	ds_bpermute_b32 v80, v89, v79
	s_waitcnt lgkmcnt(0)
	v_add_f32_e32 v71, v75, v76
	s_waitcnt lgkmcnt(0)
	v_add_f32_e32 v75, v77, v78
	s_waitcnt lgkmcnt(0)
	v_add_f32_e32 v77, v79, v80
	ds_bpermute_b32 v73, v90, v71
	ds_bpermute_b32 v76, v90, v75
	ds_bpermute_b32 v78, v90, v77
	s_and_saveexec_b64 s[12:13], s[38:39]
	s_cbranch_execz .LBB0_416
; __device__ __forceinline__ void logits_job(const Args& a, const bf16* Z, int lane, int wave) {
;     ...
;         const float rstd = 1.f / sqrtf(wave_sum(s2) * (1.f / D) + LN_EPS);
;         float mine = 0.f;
; #pragma unroll
;         for (int h = 0; h < 8; ++h) { float d = 0.f;
; #pragma unroll
;             for (int j = 0; j < 4; ++j) { const f32x4 w = ((const f32x4*)(WF + h * 1024))[64 * j + lane]; d += (v[j][0] * w[0] + v[j][1] * w[1]) + (v[j][2] * w[2] + v[j][3] * w[3]); }
;             d = wave_sum(d); if (lane == h) mine = d; }
;         if (lane < 8) { const float z = mine * rstd + cbf[lane] + bfp[lane];
;             const float e_ = __expf(-fabsf(z)), u_ = 1.f + e_; const float l1p = (u_ == 1.f) ? e_ : __logf(u_) * (e_ / (u_ - 1.f));
;             const float ls = fminf(z, 0.f) - l1p;
;             const int b = m / S, sidx = m % S; LOGF[((size_t)(b * 8 + lane)) * S + sidx] = ls; }
	global_load_dword v79, v[2:3], off
	global_load_dword v80, v[4:5], off
	v_add_f32_e32 v70, v70, v72
	s_mov_b32 s17, 0xf800000
	v_add_f32_e32 v74, v74, v99
	v_fmamk_f32 v70, v70, 0x3a800000, v91
	s_waitcnt lgkmcnt(0)
	v_add_f32_e32 v72, v77, v78
	v_add_f32_e32 v78, v100, v101
	v_cndmask_b32_e64 v74, 0, v74, s[54:55]
	v_mul_f32_e32 v81, 0x4f800000, v70
	v_cmp_gt_f32_e32 vcc, s17, v70
	v_add_f32_e32 v77, v102, v103
	v_cndmask_b32_e64 v74, v74, v78, s[52:53]
	v_cndmask_b32_e32 v70, v70, v81, vcc
	v_cndmask_b32_e64 v74, v74, v77, s[50:51]
	v_sqrt_f32_e32 v77, v70
	v_add_f32_e32 v75, v75, v76
	v_add_f32_e32 v76, v104, v105
	v_add_f32_e32 v71, v71, v73
	v_add_f32_e32 v73, v106, v107
	v_cndmask_b32_e64 v74, v74, v76, s[48:49]
	v_cndmask_b32_e64 v73, v74, v73, s[46:47]
	v_cndmask_b32_e64 v71, v73, v71, s[44:45]
	v_add_u32_e32 v73, -1, v77
	v_cndmask_b32_e64 v71, v71, v75, s[42:43]
	v_add_u32_e32 v74, 1, v77
	v_fma_f32 v75, -v73, v77, v70
	v_fma_f32 v76, -v74, v77, v70
	v_cmp_ge_f32_e64 s[56:57], 0, v75
	v_cndmask_b32_e64 v71, v71, v72, s[40:41]
	s_mov_b32 s17, 0xbfb8aa3b
	v_cndmask_b32_e64 v73, v77, v73, s[56:57]
	v_cmp_lt_f32_e64 s[56:57], 0, v76
	s_nop 1
	v_cndmask_b32_e64 v73, v73, v74, s[56:57]
	v_mul_f32_e32 v74, 0x37800000, v73
	v_cndmask_b32_e32 v73, v73, v74, vcc
	v_cmp_class_f32_e32 vcc, v70, v92
	s_nop 1
	v_cndmask_b32_e32 v70, v73, v70, vcc
	v_div_scale_f32 v73, s[18:19], v70, v70, 1.0
	v_rcp_f32_e32 v74, v73
	v_div_scale_f32 v72, vcc, 1.0, v70, 1.0
	v_fma_f32 v75, -v73, v74, 1.0
	v_fmac_f32_e32 v74, v75, v74
	v_mul_f32_e32 v75, v72, v74
	v_fma_f32 v76, -v73, v75, v72
	v_fmac_f32_e32 v75, v76, v74
	v_fma_f32 v72, -v73, v75, v72
	v_div_fmas_f32 v72, v72, v74, v75
	v_div_fixup_f32 v70, v72, v70, 1.0
	s_waitcnt vmcnt(1)
	v_fmac_f32_e32 v79, v70, v71
	s_waitcnt vmcnt(0)
	v_add_f32_e32 v70, v79, v80
	v_mul_f32_e64 v71, |v70|, s17
	v_exp_f32_e32 v71, v71
	s_nop 0
	v_add_f32_e32 v72, 1.0, v71
	v_cmp_neq_f32_e32 vcc, 1.0, v72
	s_and_saveexec_b64 s[22:23], vcc
	s_cbranch_execz .LBB0_415
	v_cmp_gt_f32_e32 vcc, s9, v72
	s_nop 1
	v_cndmask_b32_e64 v73, 0, 32, vcc
	v_ldexp_f32 v73, v72, v73
	v_log_f32_e32 v73, v73
	v_add_f32_e32 v72, -1.0, v72
	v_div_scale_f32 v75, s[18:19], v72, v72, v71
	v_mul_f32_e32 v74, 0x3f317217, v73
	v_fma_f32 v74, v73, s15, -v74
	v_rcp_f32_e32 v76, v75
	v_fmac_f32_e32 v74, 0x3377d1cf, v73
	v_fmac_f32_e32 v74, 0x3f317217, v73
	v_cmp_lt_f32_e64 s[56:57], |v73|, s16
	s_nop 1
	v_cndmask_b32_e64 v73, v73, v74, s[56:57]
	v_cndmask_b32_e32 v74, 0, v93, vcc
	v_sub_f32_e32 v73, v73, v74
	v_fma_f32 v74, -v75, v76, 1.0
	v_fmac_f32_e32 v76, v74, v76
	v_div_scale_f32 v74, vcc, v71, v72, v71
	v_mul_f32_e32 v77, v74, v76
	v_fma_f32 v78, -v75, v77, v74
	v_fmac_f32_e32 v77, v78, v76
	v_fma_f32 v74, -v75, v77, v74
	v_div_fmas_f32 v74, v74, v76, v77
	v_div_fixup_f32 v71, v74, v72, v71
	v_mul_f32_e32 v71, v73, v71
	s_branch .LBB0_415
